# v45 + non-leader work-groups issue their L1 invalidate before spinning on the barrier generation word (overlaps the wait); waves are parked and polls are sc1 so nothing refills L1 meanwhile
# speedup vs baseline: 1.0134x; 1.0023x over previous
; __device__ __forceinline__ unsigned xb_ld(unsigned* p)              { return __hip_atomic_load(p, __ATOMIC_RELAXED, __HIP_MEMORY_SCOPE_AGENT); }
; #define XB_SPIN(cond, bar) do { unsigned _sp = 0; while (cond) { __builtin_amdgcn_s_sleep(1); \
;     if ((++_sp & 255u) == 0u) { if (xb_ld(&(bar)[XB_TMO])) break; if (_sp > XB_SPIN_CAP) { atomicAdd(&(bar)[XB_TMO], 1u); break; } } } } while (0)
; __device__ __forceinline__ void xcd_barrier(const XcdBarrier& b) {
;     ...
;         } else {
;             XB_SPIN(xb_ld(&bar[XB_XGEN(b.x)]) == gen, bar);
;             __builtin_amdgcn_fence(__ATOMIC_ACQUIRE, "agent");
.LBB0_569:
	s_or_b64 exec, exec, s[12:13]
	v_cvt_f32_u32_e32 v5, v3
	s_waitcnt vmcnt(0)
	v_readfirstlane_b32 s0, v4
	v_sub_u32_e32 v4, 0, v3
	v_rcp_iflag_f32_e32 v5, v5
	v_add_u32_e32 v6, s0, v1
	v_mul_f32_e32 v5, 0x4f7ffffe, v5
	v_cvt_u32_f32_e32 v5, v5
	v_mul_lo_u32 v1, v4, v5
	v_mul_hi_u32 v1, v5, v1
	v_add_u32_e32 v1, v5, v1
	v_mul_hi_u32 v1, v6, v1
	v_mul_lo_u32 v4, v1, v3
	v_sub_u32_e32 v4, v6, v4
	v_add_u32_e32 v5, 1, v1
	v_cmp_ge_u32_e32 vcc, v4, v3
	s_nop 1
	v_cndmask_b32_e32 v1, v1, v5, vcc
	v_sub_u32_e32 v5, v4, v3
	v_cndmask_b32_e32 v4, v4, v5, vcc
	v_add_u32_e32 v5, 1, v1
	v_cmp_ge_u32_e32 vcc, v4, v3
	v_add_u32_e32 v4, 1, v6
	s_nop 0
	v_cndmask_b32_e32 v1, v1, v5, vcc
	v_mul_lo_u32 v5, v3, v1
	v_add_u32_e32 v3, v5, v3
	v_cmp_ne_u32_e32 vcc, v4, v3
	s_and_saveexec_b64 s[0:1], vcc
	s_xor_b64 s[8:9], exec, s[0:1]
	s_cbranch_execz .LBB0_583
	s_waitcnt lgkmcnt(0)
	buffer_inv sc1
	v_readlane_b32 s14, v254, 31
	v_readlane_b32 s15, v254, 32
	s_nop 4
	global_load_dword v2, v0, s[14:15] sc1
	s_waitcnt vmcnt(0)
	v_cmp_eq_u32_e32 vcc, v2, v1
	s_and_saveexec_b64 s[12:13], vcc
	s_cbranch_execz .LBB0_582
	s_mov_b32 s0, 1
	s_mov_b64 s[16:17], 0
	s_branch .LBB0_573

; __device__ __forceinline__ unsigned xb_ld(unsigned* p)              { return __hip_atomic_load(p, __ATOMIC_RELAXED, __HIP_MEMORY_SCOPE_AGENT); }
; #define XB_SPIN(cond, bar) do { unsigned _sp = 0; while (cond) { __builtin_amdgcn_s_sleep(1); \
;     if ((++_sp & 255u) == 0u) { if (xb_ld(&(bar)[XB_TMO])) break; if (_sp > XB_SPIN_CAP) { atomicAdd(&(bar)[XB_TMO], 1u); break; } } } } while (0)
; __device__ __forceinline__ void xcd_barrier(const XcdBarrier& b) {
;     ...
;         } else {
;             XB_SPIN(xb_ld(&bar[XB_XGEN(b.x)]) == gen, bar);
;             __builtin_amdgcn_fence(__ATOMIC_ACQUIRE, "agent");
.LBB0_630:
	s_or_b64 exec, exec, s[14:15]
	v_cvt_f32_u32_e32 v5, v3
	s_waitcnt vmcnt(0)
	v_readfirstlane_b32 s0, v4
	v_sub_u32_e32 v4, 0, v3
	v_rcp_iflag_f32_e32 v5, v5
	v_add_u32_e32 v6, s0, v1
	v_mul_f32_e32 v5, 0x4f7ffffe, v5
	v_cvt_u32_f32_e32 v5, v5
	v_mul_lo_u32 v1, v4, v5
	v_mul_hi_u32 v1, v5, v1
	v_add_u32_e32 v1, v5, v1
	v_mul_hi_u32 v1, v6, v1
	v_mul_lo_u32 v4, v1, v3
	v_sub_u32_e32 v4, v6, v4
	v_add_u32_e32 v5, 1, v1
	v_cmp_ge_u32_e32 vcc, v4, v3
	s_nop 1
	v_cndmask_b32_e32 v1, v1, v5, vcc
	v_sub_u32_e32 v5, v4, v3
	v_cndmask_b32_e32 v4, v4, v5, vcc
	v_add_u32_e32 v5, 1, v1
	v_cmp_ge_u32_e32 vcc, v4, v3
	v_add_u32_e32 v4, 1, v6
	s_nop 0
	v_cndmask_b32_e32 v1, v1, v5, vcc
	v_mul_lo_u32 v5, v3, v1
	v_add_u32_e32 v3, v5, v3
	v_cmp_ne_u32_e32 vcc, v4, v3
	s_and_saveexec_b64 s[0:1], vcc
	s_xor_b64 s[12:13], exec, s[0:1]
	s_cbranch_execz .LBB0_644
	s_waitcnt lgkmcnt(0)
	buffer_inv sc1
	v_readlane_b32 s16, v254, 31
	v_readlane_b32 s17, v254, 32
	s_nop 4
	global_load_dword v2, v0, s[16:17] sc1
	s_waitcnt vmcnt(0)
	v_cmp_eq_u32_e32 vcc, v2, v1
	s_and_saveexec_b64 s[14:15], vcc
	s_cbranch_execz .LBB0_643
	s_mov_b32 s0, 1
	s_mov_b64 s[18:19], 0
	s_branch .LBB0_634

; __device__ __forceinline__ unsigned xb_ld(unsigned* p)              { return __hip_atomic_load(p, __ATOMIC_RELAXED, __HIP_MEMORY_SCOPE_AGENT); }
; #define XB_SPIN(cond, bar) do { unsigned _sp = 0; while (cond) { __builtin_amdgcn_s_sleep(1); \
;     if ((++_sp & 255u) == 0u) { if (xb_ld(&(bar)[XB_TMO])) break; if (_sp > XB_SPIN_CAP) { atomicAdd(&(bar)[XB_TMO], 1u); break; } } } } while (0)
; __device__ __forceinline__ void xcd_barrier(const XcdBarrier& b) {
;     ...
;         } else {
;             XB_SPIN(xb_ld(&bar[XB_XGEN(b.x)]) == gen, bar);
;             __builtin_amdgcn_fence(__ATOMIC_ACQUIRE, "agent");
.LBB0_1134:
	s_or_b64 exec, exec, s[10:11]
	v_cvt_f32_u32_e32 v5, v3
	s_waitcnt vmcnt(0)
	v_readfirstlane_b32 s0, v4
	v_sub_u32_e32 v4, 0, v3
	v_rcp_iflag_f32_e32 v5, v5
	v_add_u32_e32 v6, s0, v1
	v_mul_f32_e32 v5, 0x4f7ffffe, v5
	v_cvt_u32_f32_e32 v5, v5
	v_mul_lo_u32 v1, v4, v5
	v_mul_hi_u32 v1, v5, v1
	v_add_u32_e32 v1, v5, v1
	v_mul_hi_u32 v1, v6, v1
	v_mul_lo_u32 v4, v1, v3
	v_sub_u32_e32 v4, v6, v4
	v_add_u32_e32 v5, 1, v1
	v_cmp_ge_u32_e32 vcc, v4, v3
	s_nop 1
	v_cndmask_b32_e32 v1, v1, v5, vcc
	v_sub_u32_e32 v5, v4, v3
	v_cndmask_b32_e32 v4, v4, v5, vcc
	v_add_u32_e32 v5, 1, v1
	v_cmp_ge_u32_e32 vcc, v4, v3
	v_add_u32_e32 v4, 1, v6
	s_nop 0
	v_cndmask_b32_e32 v1, v1, v5, vcc
	v_mul_lo_u32 v5, v3, v1
	v_add_u32_e32 v3, v5, v3
	v_cmp_ne_u32_e32 vcc, v4, v3
	s_and_saveexec_b64 s[0:1], vcc
	s_xor_b64 s[8:9], exec, s[0:1]
	s_cbranch_execz .LBB0_1148
	s_waitcnt lgkmcnt(0)
	buffer_inv sc1
	v_readlane_b32 s12, v254, 31
	v_readlane_b32 s13, v254, 32
	s_nop 4
	global_load_dword v2, v0, s[12:13] sc1
	s_waitcnt vmcnt(0)
	v_cmp_eq_u32_e32 vcc, v2, v1
	s_and_saveexec_b64 s[10:11], vcc
	s_cbranch_execz .LBB0_1147
	s_mov_b32 s0, 1
	s_mov_b64 s[14:15], 0
	s_branch .LBB0_1138

; __device__ __forceinline__ unsigned xb_ld(unsigned* p)              { return __hip_atomic_load(p, __ATOMIC_RELAXED, __HIP_MEMORY_SCOPE_AGENT); }
; #define XB_SPIN(cond, bar) do { unsigned _sp = 0; while (cond) { __builtin_amdgcn_s_sleep(1); \
;     if ((++_sp & 255u) == 0u) { if (xb_ld(&(bar)[XB_TMO])) break; if (_sp > XB_SPIN_CAP) { atomicAdd(&(bar)[XB_TMO], 1u); break; } } } } while (0)
; __device__ __forceinline__ void xcd_barrier(const XcdBarrier& b) {
;     ...
;         } else {
;             XB_SPIN(xb_ld(&bar[XB_XGEN(b.x)]) == gen, bar);
;             __builtin_amdgcn_fence(__ATOMIC_ACQUIRE, "agent");
.LBB0_2078:
	s_or_b64 exec, exec, s[8:9]
	v_cvt_f32_u32_e32 v5, v3
	s_waitcnt vmcnt(0)
	v_readfirstlane_b32 s3, v4
	v_sub_u32_e32 v4, 0, v3
	v_rcp_iflag_f32_e32 v5, v5
	v_add_u32_e32 v6, s3, v1
	v_mul_f32_e32 v5, 0x4f7ffffe, v5
	v_cvt_u32_f32_e32 v5, v5
	v_mul_lo_u32 v1, v4, v5
	v_mul_hi_u32 v1, v5, v1
	v_add_u32_e32 v1, v5, v1
	v_mul_hi_u32 v1, v6, v1
	v_mul_lo_u32 v4, v1, v3
	v_sub_u32_e32 v4, v6, v4
	v_add_u32_e32 v5, 1, v1
	v_cmp_ge_u32_e32 vcc, v4, v3
	s_nop 1
	v_cndmask_b32_e32 v1, v1, v5, vcc
	v_sub_u32_e32 v5, v4, v3
	v_cndmask_b32_e32 v4, v4, v5, vcc
	v_add_u32_e32 v5, 1, v1
	v_cmp_ge_u32_e32 vcc, v4, v3
	v_add_u32_e32 v4, 1, v6
	s_nop 0
	v_cndmask_b32_e32 v1, v1, v5, vcc
	v_mul_lo_u32 v5, v3, v1
	v_add_u32_e32 v3, v5, v3
	v_cmp_ne_u32_e32 vcc, v4, v3
	s_and_saveexec_b64 s[6:7], vcc
	s_xor_b64 s[6:7], exec, s[6:7]
	s_cbranch_execz .LBB0_2092
	s_waitcnt lgkmcnt(0)
	buffer_inv sc1
	v_readlane_b32 s10, v254, 31
	v_readlane_b32 s11, v254, 32
	s_nop 4
	global_load_dword v2, v0, s[10:11] sc1
	s_waitcnt vmcnt(0)
	v_cmp_eq_u32_e32 vcc, v2, v1
	s_and_saveexec_b64 s[8:9], vcc
	s_cbranch_execz .LBB0_2091
	s_mov_b32 s3, 1
	s_mov_b64 s[12:13], 0
	s_branch .LBB0_2082

; __device__ __forceinline__ unsigned xb_ld(unsigned* p)              { return __hip_atomic_load(p, __ATOMIC_RELAXED, __HIP_MEMORY_SCOPE_AGENT); }
; #define XB_SPIN(cond, bar) do { unsigned _sp = 0; while (cond) { __builtin_amdgcn_s_sleep(1); \
;     if ((++_sp & 255u) == 0u) { if (xb_ld(&(bar)[XB_TMO])) break; if (_sp > XB_SPIN_CAP) { atomicAdd(&(bar)[XB_TMO], 1u); break; } } } } while (0)
; __device__ __forceinline__ void xcd_barrier(const XcdBarrier& b) {
;     ...
;         } else {
;             XB_SPIN(xb_ld(&bar[XB_XGEN(b.x)]) == gen, bar);
;             __builtin_amdgcn_fence(__ATOMIC_ACQUIRE, "agent");
.LBB0_2180:
	s_or_b64 exec, exec, s[10:11]
	v_cvt_f32_u32_e32 v5, v3
	s_waitcnt vmcnt(0)
	v_readfirstlane_b32 s3, v4
	v_sub_u32_e32 v4, 0, v3
	v_rcp_iflag_f32_e32 v5, v5
	v_add_u32_e32 v6, s3, v1
	v_mul_f32_e32 v5, 0x4f7ffffe, v5
	v_cvt_u32_f32_e32 v5, v5
	v_mul_lo_u32 v1, v4, v5
	v_mul_hi_u32 v1, v5, v1
	v_add_u32_e32 v1, v5, v1
	v_mul_hi_u32 v1, v6, v1
	v_mul_lo_u32 v4, v1, v3
	v_sub_u32_e32 v4, v6, v4
	v_add_u32_e32 v5, 1, v1
	v_cmp_ge_u32_e32 vcc, v4, v3
	s_nop 1
	v_cndmask_b32_e32 v1, v1, v5, vcc
	v_sub_u32_e32 v5, v4, v3
	v_cndmask_b32_e32 v4, v4, v5, vcc
	v_add_u32_e32 v5, 1, v1
	v_cmp_ge_u32_e32 vcc, v4, v3
	v_add_u32_e32 v4, 1, v6
	s_nop 0
	v_cndmask_b32_e32 v1, v1, v5, vcc
	v_mul_lo_u32 v5, v3, v1
	v_add_u32_e32 v3, v5, v3
	v_cmp_ne_u32_e32 vcc, v4, v3
	s_and_saveexec_b64 s[4:5], vcc
	s_xor_b64 s[8:9], exec, s[4:5]
	s_cbranch_execz .LBB0_2194
	s_waitcnt lgkmcnt(0)
	buffer_inv sc1
	v_readlane_b32 s12, v254, 31
	v_readlane_b32 s13, v254, 32
	s_nop 4
	global_load_dword v2, v0, s[12:13] sc1
	s_waitcnt vmcnt(0)
	v_cmp_eq_u32_e32 vcc, v2, v1
	s_and_saveexec_b64 s[10:11], vcc
	s_cbranch_execz .LBB0_2193
	s_mov_b32 s3, 1
	s_mov_b64 s[14:15], 0
	s_branch .LBB0_2184
